# speedup vs baseline: 1.0548x; 1.0082x over previous
.LBB0_1011:
	s_add_i32 s0, s49, s50
	s_lshl_b32 s27, s54, 14
	v_cmp_eq_u32_e32 vcc, 0, v56
	v_mov_b32_e32 v56, 1
	s_and_saveexec_b64 s[28:29], vcc
	s_cbranch_execz .LBB0_1019
	s_add_i32 s30, s0, 64
	v_cmp_le_i32_e32 vcc, s30, v48
	v_mov_b32_e32 v56, 0
	s_and_saveexec_b64 s[30:31], vcc
	s_cbranch_execz .LBB0_1018
	v_add_u32_e32 v2, s27, v53
	v_add_u32_e32 v76, v2, v49
	v_add_u32_e32 v77, v2, v50
	ds_read_b128 v[56:59], v76
	ds_read_b128 v[60:63], v76 offset:2048
	ds_read_b128 v[64:67], v77
	ds_read_b128 v[72:75], v77 offset:4096
	s_waitcnt lgkmcnt(3)
	v_mfma_f32_16x16x32_bf16 v[56:59], v[56:59], v[20:23], 0
	ds_read_b128 v[68:71], v77 offset:2048
	s_add_i32 s36, s0, 0x7f
	v_cmp_ge_u32_e32 vcc, s36, v48
	s_waitcnt lgkmcnt(2)
	v_mfma_f32_16x16x32_bf16 v[56:59], v[64:67], v[24:27], v[56:59]
	ds_read_b128 v[64:67], v76 offset:4096
	v_mfma_f32_16x16x32_bf16 v[60:63], v[60:63], v[20:23], 0
	s_nop 5
	v_exp_f32_e64 v166, -v56
	v_exp_f32_e64 v167, -v57
	v_exp_f32_e64 v168, -v58
	s_waitcnt lgkmcnt(1)
	v_mfma_f32_16x16x32_bf16 v[60:63], v[68:71], v[24:27], v[60:63]
	ds_read_b128 v[68:71], v76 offset:6144
	ds_read_b128 v[76:79], v77 offset:6144
	v_exp_f32_e64 v169, -v59
	s_waitcnt lgkmcnt(2)
	v_mfma_f32_16x16x32_bf16 v[64:67], v[64:67], v[20:23], 0
	s_nop 2
	v_exp_f32_e64 v170, -v60
	v_exp_f32_e64 v171, -v61
	v_exp_f32_e64 v172, -v62
	v_mfma_f32_16x16x32_bf16 v[146:149], v[72:75], v[24:27], v[64:67]
	v_exp_f32_e64 v173, -v63
	s_waitcnt lgkmcnt(1)
	v_mfma_f32_16x16x32_bf16 v[64:67], v[68:71], v[20:23], 0
	s_waitcnt lgkmcnt(0)
	v_mfma_f32_16x16x32_bf16 v[150:153], v[76:79], v[24:27], v[64:67]
	s_nop 2
	v_exp_f32_e64 v174, -v146
	v_exp_f32_e64 v175, -v147
	v_exp_f32_e64 v176, -v148
	v_exp_f32_e64 v177, -v149
	s_nop 0
	v_exp_f32_e64 v178, -v150
	v_exp_f32_e64 v179, -v151
	v_exp_f32_e64 v180, -v152
	v_exp_f32_e64 v181, -v153
	v_pk_add_f32 v[182:183], v[166:167], 1.0 op_sel_hi:[1,0]
	v_pk_add_f32 v[184:185], v[168:169], 1.0 op_sel_hi:[1,0]
	v_pk_add_f32 v[186:187], v[170:171], 1.0 op_sel_hi:[1,0]
	v_pk_add_f32 v[188:189], v[172:173], 1.0 op_sel_hi:[1,0]
	v_pk_add_f32 v[190:191], v[174:175], 1.0 op_sel_hi:[1,0]
	v_pk_add_f32 v[192:193], v[176:177], 1.0 op_sel_hi:[1,0]
	v_pk_add_f32 v[194:195], v[178:179], 1.0 op_sel_hi:[1,0]
	v_pk_add_f32 v[196:197], v[180:181], 1.0 op_sel_hi:[1,0]
	v_rcp_f32_e32 v198, v182
	v_rcp_f32_e32 v199, v183
	v_rcp_f32_e32 v200, v184
	v_rcp_f32_e32 v201, v185
	v_rcp_f32_e32 v202, v186
	v_rcp_f32_e32 v203, v187
	v_rcp_f32_e32 v204, v188
	v_rcp_f32_e32 v205, v189
	v_rcp_f32_e32 v206, v190
	v_rcp_f32_e32 v207, v191
	v_rcp_f32_e32 v208, v192
	v_rcp_f32_e32 v209, v193
	v_rcp_f32_e32 v210, v194
	v_rcp_f32_e32 v211, v195
	v_rcp_f32_e32 v212, v196
	v_rcp_f32_e32 v213, v197
	v_pk_add_f32 v[214:215], v[198:199], 1.0 op_sel_hi:[1,0] neg_lo:[1,0] neg_hi:[1,0]
	v_pk_add_f32 v[216:217], v[200:201], 1.0 op_sel_hi:[1,0] neg_lo:[1,0] neg_hi:[1,0]
	v_pk_add_f32 v[218:219], v[202:203], 1.0 op_sel_hi:[1,0] neg_lo:[1,0] neg_hi:[1,0]
	v_pk_add_f32 v[220:221], v[204:205], 1.0 op_sel_hi:[1,0] neg_lo:[1,0] neg_hi:[1,0]
	v_pk_add_f32 v[222:223], v[206:207], 1.0 op_sel_hi:[1,0] neg_lo:[1,0] neg_hi:[1,0]
	v_pk_add_f32 v[224:225], v[208:209], 1.0 op_sel_hi:[1,0] neg_lo:[1,0] neg_hi:[1,0]
	v_pk_add_f32 v[226:227], v[210:211], 1.0 op_sel_hi:[1,0] neg_lo:[1,0] neg_hi:[1,0]
	v_pk_add_f32 v[228:229], v[212:213], 1.0 op_sel_hi:[1,0] neg_lo:[1,0] neg_hi:[1,0]
	s_and_saveexec_b64 s[36:37], vcc
	s_cbranch_execz .Lpk_join
	v_cmp_lt_i32_e64 s[66:67], 0, v54
	v_cmp_lt_i32_e64 s[68:69], 1, v54
	v_cmp_lt_i32_e64 s[70:71], 2, v54
	v_cmp_lt_i32_e64 s[72:73], 3, v54
	v_cndmask_b32_e64 v198, 0, v198, s[66:67]
	v_cndmask_b32_e64 v214, 1.0, v214, s[66:67]
	v_cndmask_b32_e64 v199, 0, v199, s[68:69]
	v_cndmask_b32_e64 v215, 1.0, v215, s[68:69]
	v_cndmask_b32_e64 v200, 0, v200, s[70:71]
	v_cndmask_b32_e64 v216, 1.0, v216, s[70:71]
	v_cndmask_b32_e64 v201, 0, v201, s[72:73]
	v_cndmask_b32_e64 v217, 1.0, v217, s[72:73]
	v_cmp_lt_i32_e64 s[66:67], 4, v54
	v_cmp_lt_i32_e64 s[68:69], 5, v54
	v_cmp_lt_i32_e64 s[70:71], 6, v54
	v_cmp_lt_i32_e64 s[72:73], 7, v54
	v_cndmask_b32_e64 v202, 0, v202, s[66:67]
	v_cndmask_b32_e64 v218, 1.0, v218, s[66:67]
	v_cndmask_b32_e64 v203, 0, v203, s[68:69]
	v_cndmask_b32_e64 v219, 1.0, v219, s[68:69]
	v_cndmask_b32_e64 v204, 0, v204, s[70:71]
	v_cndmask_b32_e64 v220, 1.0, v220, s[70:71]
	v_cndmask_b32_e64 v205, 0, v205, s[72:73]
	v_cndmask_b32_e64 v221, 1.0, v221, s[72:73]
	v_cmp_lt_i32_e64 s[66:67], 8, v54
	v_cmp_lt_i32_e64 s[68:69], 9, v54
	v_cmp_lt_i32_e64 s[70:71], 10, v54
	v_cmp_lt_i32_e64 s[72:73], 11, v54
	v_cndmask_b32_e64 v206, 0, v206, s[66:67]
	v_cndmask_b32_e64 v222, 1.0, v222, s[66:67]
	v_cndmask_b32_e64 v207, 0, v207, s[68:69]
	v_cndmask_b32_e64 v223, 1.0, v223, s[68:69]
	v_cndmask_b32_e64 v208, 0, v208, s[70:71]
	v_cndmask_b32_e64 v224, 1.0, v224, s[70:71]
	v_cndmask_b32_e64 v209, 0, v209, s[72:73]
	v_cndmask_b32_e64 v225, 1.0, v225, s[72:73]
	v_cmp_lt_i32_e64 s[66:67], 12, v54
	v_cmp_lt_i32_e64 s[68:69], 13, v54
	v_cmp_lt_i32_e64 s[70:71], 14, v54
	v_cmp_lt_i32_e64 s[72:73], 15, v54
	v_cndmask_b32_e64 v210, 0, v210, s[66:67]
	v_cndmask_b32_e64 v226, 1.0, v226, s[66:67]
	v_cndmask_b32_e64 v211, 0, v211, s[68:69]
	v_cndmask_b32_e64 v227, 1.0, v227, s[68:69]
	v_cndmask_b32_e64 v212, 0, v212, s[70:71]
	v_cndmask_b32_e64 v228, 1.0, v228, s[70:71]
	v_cndmask_b32_e64 v213, 0, v213, s[72:73]
	v_cndmask_b32_e64 v229, 1.0, v229, s[72:73]
.Lpk_join:
	s_or_b64 exec, exec, s[36:37]
	v_mov_b32_e32 v181, 1.0
	v_mov_b32_e32 v180, v229
	v_mul_f32_e32 v179, v180, v228
	v_mul_f32_e32 v178, v179, v227
	v_mul_f32_e32 v177, v178, v226
	v_mul_f32_e32 v176, v177, v225
	v_mul_f32_e32 v175, v176, v224
	v_mul_f32_e32 v174, v175, v223
	v_mul_f32_e32 v173, v174, v222
	v_mul_f32_e32 v172, v173, v221
	v_mul_f32_e32 v171, v172, v220
	v_mul_f32_e32 v170, v171, v219
	v_mul_f32_e32 v169, v170, v218
	v_mul_f32_e32 v168, v169, v217
	v_mul_f32_e32 v167, v168, v216
	v_mul_f32_e32 v166, v167, v215
	v_mul_f32_e32 v240, v166, v214
	s_nop 0
	ds_bpermute_b32 v241, v162, v240
	ds_bpermute_b32 v242, v163, v240
	ds_bpermute_b32 v243, v164, v240
	s_waitcnt lgkmcnt(2)
	v_cndmask_b32_e64 v244, 1.0, v241, s[10:11]
	s_waitcnt lgkmcnt(1)
	v_mul_f32_e32 v245, v244, v242
	v_cndmask_b32_e64 v244, v244, v245, s[4:5]
	s_waitcnt lgkmcnt(0)
	v_mul_f32_e32 v245, v244, v243
	v_cndmask_b32_e64 v244, v244, v245, s[6:7]
	v_mul_f32_e32 v230, v55, v244
	v_mov_b32_e32 v231, v230
	v_pk_mul_f32 v[182:183], v[166:167], v[230:231]
	v_pk_mul_f32 v[184:185], v[168:169], v[230:231]
	v_pk_mul_f32 v[186:187], v[170:171], v[230:231]
	v_pk_mul_f32 v[188:189], v[172:173], v[230:231]
	v_pk_mul_f32 v[190:191], v[174:175], v[230:231]
	v_pk_mul_f32 v[192:193], v[176:177], v[230:231]
	v_pk_mul_f32 v[194:195], v[178:179], v[230:231]
	v_pk_mul_f32 v[196:197], v[180:181], v[230:231]
	v_pk_mul_f32 v[182:183], v[198:199], v[182:183]
	v_pk_mul_f32 v[184:185], v[200:201], v[184:185]
	v_pk_mul_f32 v[186:187], v[202:203], v[186:187]
	v_pk_mul_f32 v[188:189], v[204:205], v[188:189]
	v_pk_mul_f32 v[190:191], v[206:207], v[190:191]
	v_pk_mul_f32 v[192:193], v[208:209], v[192:193]
	v_pk_mul_f32 v[194:195], v[210:211], v[194:195]
	v_pk_mul_f32 v[196:197], v[212:213], v[196:197]
	v_cvt_pk_bf16_f32 v232, v182, v183
	v_cvt_pk_bf16_f32 v233, v184, v185
	v_cvt_pk_bf16_f32 v234, v186, v187
	v_cvt_pk_bf16_f32 v235, v188, v189
	v_cvt_pk_bf16_f32 v236, v190, v191
	v_cvt_pk_bf16_f32 v237, v192, v193
	v_cvt_pk_bf16_f32 v238, v194, v195
	v_cvt_pk_bf16_f32 v239, v196, v197
	v_add_u32_e32 v81, v2, v51
	ds_read_b128 v[60:63], v81 offset:8192
	ds_read_b128 v[72:75], v81 offset:10240
	v_add_u32_e32 v2, v2, v52
	ds_read_b128 v[64:67], v2 offset:8192
	s_waitcnt lgkmcnt(2)
	v_mfma_f32_16x16x32_bf16 v[8:11], v[60:63], v[232:235], v[8:11]
	ds_read_b128 v[60:63], v2 offset:10240
	v_mul_f32_e32 v246, v242, v243
	v_mul_f32_e32 v247, v240, v241
	s_waitcnt lgkmcnt(2)
	v_mfma_f32_16x16x32_bf16 v[12:15], v[72:75], v[232:235], v[12:15]
	s_waitcnt lgkmcnt(1)
	v_mfma_f32_16x16x32_bf16 v[8:11], v[64:67], v[236:239], v[8:11]
	s_waitcnt lgkmcnt(0)
	v_mfma_f32_16x16x32_bf16 v[12:15], v[60:63], v[236:239], v[12:15]
	ds_read_b128 v[60:63], v81 offset:12288
	ds_read_b128 v[64:67], v81 offset:14336
	s_waitcnt lgkmcnt(1)
	v_mfma_f32_16x16x32_bf16 v[16:19], v[60:63], v[232:235], v[16:19]
	ds_read_b128 v[60:63], v2 offset:12288
	ds_read_b128 v[72:75], v2 offset:14336
	s_waitcnt lgkmcnt(2)
	v_mfma_f32_16x16x32_bf16 v[4:7], v[64:67], v[232:235], v[4:7]
	v_mul_f32_e32 v246, v246, v247
	v_mul_f32_e32 v55, v55, v246
	s_waitcnt lgkmcnt(1)
	v_mfma_f32_16x16x32_bf16 v[16:19], v[60:63], v[236:239], v[16:19]
	v_cmp_eq_f32_e32 vcc, 0, v55
	s_cmp_eq_u64 vcc, exec
	s_cselect_b64 s[36:37], -1, 0
	s_waitcnt lgkmcnt(0)
	v_mfma_f32_16x16x32_bf16 v[4:7], v[72:75], v[236:239], v[4:7]
	v_cndmask_b32_e64 v56, 0, 1, s[36:37]
